# next phase's instructions touched with PC-relative loads at each grid-barrier exit (bulk pull of code into L2)
# speedup vs baseline: 1.0024x; 1.0024x over previous
; __device__ __forceinline__ float bf_lo(unsigned u) { return __uint_as_float(u << 16); }
; __device__ __forceinline__ float bf_hi(unsigned u) { return __uint_as_float(u & 0xffff0000u); }
; __device__ __forceinline__ int vblk() { return (int)blockIdx.x * 2 + half_id(); }
; __device__ __forceinline__ int vgrid() { return (int)gridDim.x * 2; }
; __device__ void phase_modnorm(const Params& p, const float* __restrict__ src, const bf16_t* __restrict__ srcb, const float* __restrict__ g, int shift_idx, int scale_idx, bf16_t* __restrict__ dst) {
;     const int tid_ = TIDX; const int lane = tid_ & 63, wave = tid_ >> 6;
;     const float* mod = (const float*)(p.ws + OFF_MOD);
;     for (int tok = vblk() * 4 + wave; tok < NTOK; tok += vgrid() * 4) {
;         const int b = tok >> 11;
;         const float* xr = src + (size_t)tok * DM;
;         f32x4 v[4];
;         float ss = 0.f;
; #pragma unroll
;         for (int c = 0; c < 4; c++) {
;             if (srcb) {
;                 const u32x2 w = *(const u32x2*)(srcb + (size_t)tok * DM + c * 256 + lane * 4);
;                 v[c] = (f32x4){bf_lo(w.x), bf_hi(w.x), bf_lo(w.y), bf_hi(w.y)};
;             } else v[c] = *(const f32x4*)(xr + c * 256 + lane * 4);
;             ss += v[c][0] * v[c][0] + v[c][1] * v[c][1] + v[c][2] * v[c][2] + v[c][3] * v[c][3];
;         }
;         ss = wave_sum(ss);
;         const float rstd = rsqrtf(ss * (1.f / 1024.f) + 1e-6f);
; __device__ __forceinline__ void xcd_barrier(const XcdBarrier& b) {
;     ...
;     __syncthreads();
.LBB0_234:
	s_or_b64 exec, exec, s[4:5]
	s_getpc_b64 s[98:99]
	v_lshlrev_b32_e32 v250, 4, v158
	v_mov_b32_e32 v251, 0
	v_lshl_add_u64 v[250:251], s[98:99], 0, v[250:251]
	v_and_b32_e32 v250, -16, v250
	global_load_dwordx4 v[252:255], v[250:251], off
	v_lshl_add_u64 v[250:251], 64, 7, v[250:251]
	global_load_dwordx4 v[252:255], v[250:251], off
	v_lshl_add_u64 v[250:251], 64, 7, v[250:251]
	global_load_dwordx4 v[252:255], v[250:251], off
	v_lshl_add_u64 v[250:251], 64, 7, v[250:251]
	global_load_dwordx4 v[252:255], v[250:251], off
	v_readfirstlane_b32 s0, v158
	v_readlane_b32 s1, v222, 0
	s_lshr_b32 s0, s0, 6
	s_mov_b64 s[6:7], s[80:81]
	v_mov_b32_e32 v18, v158
	s_lshl_b32 s28, s1, 3
	s_and_b32 s0, s0, 0x3fffffc
	s_waitcnt lgkmcnt(0)
	s_barrier
	s_getpc_b64 s[98:99]
	v_lshlrev_b32_e32 v250, 4, v158
	v_mov_b32_e32 v251, 0
	v_lshl_add_u64 v[250:251], s[98:99], 0, v[250:251]
	v_and_b32_e32 v250, -16, v250
	global_load_dwordx4 v[252:255], v[250:251], off
	v_lshl_add_u64 v[250:251], 64, 7, v[250:251]
	global_load_dwordx4 v[252:255], v[250:251], off
	v_lshl_add_u64 v[250:251], 64, 7, v[250:251]
	global_load_dwordx4 v[252:255], v[250:251], off
	v_lshl_add_u64 v[250:251], 64, 7, v[250:251]
	global_load_dwordx4 v[252:255], v[250:251], off
	s_add_i32 s0, s0, s28
	v_lshrrev_b32_e32 v0, 6, v18
	v_and_or_b32 v16, v0, 3, s0
	s_movk_i32 s0, 0x4000
	v_cmp_gt_i32_e32 vcc, s0, v16
	v_mbcnt_lo_u32_b32 v30, -1, 0
	s_and_saveexec_b64 s[4:5], vcc
	s_cbranch_execz .LBB0_237
	s_load_dwordx2 s[0:1], s[6:7], 0x28
	s_load_dwordx2 s[10:11], s[6:7], 0xd8
	v_lshlrev_b32_e32 v0, 2, v18
	v_and_b32_e32 v24, 0xfc, v0
	v_lshlrev_b32_e32 v17, 2, v24
	s_waitcnt lgkmcnt(0)
	global_load_dwordx4 v[0:3], v17, s[0:1]
	global_load_dwordx4 v[4:7], v17, s[0:1] offset:1024
	global_load_dwordx4 v[8:11], v17, s[0:1] offset:2048
	global_load_dwordx4 v[12:15], v17, s[0:1] offset:3072
	v_mbcnt_hi_u32_b32 v17, -1, v30
	v_and_b32_e32 v20, 64, v17
	v_add_u32_e32 v20, 64, v20
	v_xor_b32_e32 v21, 32, v17
	v_cmp_lt_i32_e32 vcc, v21, v20
	s_load_dwordx2 s[0:1], s[6:7], 0x0
	s_add_u32 s6, s10, 0x4000
	v_cndmask_b32_e32 v21, v17, v21, vcc
	v_lshlrev_b32_e32 v31, 2, v21
	v_xor_b32_e32 v21, 16, v17
	v_cmp_lt_i32_e32 vcc, v21, v20
	v_and_b32_e32 v18, 63, v18
	s_addc_u32 s7, s11, 0
	v_cndmask_b32_e32 v21, v17, v21, vcc
	v_lshlrev_b32_e32 v32, 2, v21
	v_xor_b32_e32 v21, 8, v17
	v_cmp_lt_i32_e32 vcc, v21, v20
	s_lshl_b32 s8, s76, 3
	v_mov_b32_e32 v19, 0
	v_cndmask_b32_e32 v21, v17, v21, vcc
	v_lshlrev_b32_e32 v33, 2, v21
	v_xor_b32_e32 v21, 4, v17
	v_cmp_lt_i32_e32 vcc, v21, v20
	v_or_b32_e32 v26, 0x100, v24
	v_or_b32_e32 v28, 0x200, v24
	v_cndmask_b32_e32 v21, v17, v21, vcc
	v_lshlrev_b32_e32 v34, 2, v21
	v_xor_b32_e32 v21, 2, v17
	v_cmp_lt_i32_e32 vcc, v21, v20
	v_or_b32_e32 v38, 0x300, v24
	s_mov_b64 s[2:3], 0x1c00000
	v_cndmask_b32_e32 v21, v17, v21, vcc
	v_lshlrev_b32_e32 v35, 2, v21
	v_xor_b32_e32 v21, 1, v17
	v_cmp_lt_i32_e32 vcc, v21, v20
	s_ashr_i32 s9, s8, 31
	s_lshl_b64 s[14:15], s[8:9], 12
	v_cndmask_b32_e32 v17, v17, v21, vcc
	v_lshlrev_b32_e32 v36, 2, v17
	v_ashrrev_i32_e32 v17, 31, v16
	v_lshlrev_b64 v[20:21], 11, v[16:17]
	v_lshlrev_b64 v[22:23], 12, v[16:17]
	v_lshl_or_b32 v20, v18, 3, v20
	v_lshl_or_b32 v22, v18, 4, v22
	v_lshl_add_u64 v[20:21], s[10:11], 0, v[20:21]
	s_waitcnt lgkmcnt(0)
	v_lshl_add_u64 v[22:23], s[0:1], 0, v[22:23]
	s_mov_b64 s[0:1], 0xc00
	v_lshl_add_u64 v[20:21], v[20:21], 0, s[2:3]
	s_lshl_b64 s[10:11], s[8:9], 11
	v_lshl_add_u64 v[22:23], v[22:23], 0, s[0:1]
	s_mov_b64 s[16:17], 0
	v_mov_b32_e32 v17, 0x358637bd
	s_mov_b32 s0, 0x800000
	s_mov_b64 s[18:19], 0x1000
	v_lshlrev_b32_e32 v18, 2, v24
	v_lshlrev_b32_e32 v24, 2, v26
	v_mov_b32_e32 v25, v19
	v_lshlrev_b32_e32 v26, 2, v28
	v_mov_b32_e32 v27, v19
	v_lshlrev_b32_e32 v28, 2, v38
	v_mov_b32_e32 v29, v19
	s_movk_i32 s1, 0x3fff

; #define TIDX512 launder_i((int)threadIdx.x)
; __device__ void phaseC(const Params& p, char* lds) {
;     const int tid_ = TIDX512; const int lane = tid_ & 63, wave = tid_ >> 6;
;     const int wr = wave >> 2, wc = wave & 3, r = lane & 15, q = lane >> 4;
;     const bf16_t* H = (const bf16_t*)(p.ws + OFF_H);
;     const bf16_t* W = (const bf16_t*)(p.ws + OFF_WIN);
;     bf16_t* Z = (bf16_t*)(p.ws + OFF_Z);
;     const float* cs = (const float*)(p.ws + OFF_ROPE);
;     constexpr int NTN = (ZC + 255) / 256;
;     TileIter tit(NTN, lds);
;     int bm, bn;
;     while (tit.next(bm, bn)) {
;         const int m0 = bm * 256, n0 = bn * 256;
; __device__ __forceinline__ void xcd_barrier(const XcdBarrier& b) {
;     ...
;     __syncthreads();
.LBB0_288:
	s_or_b64 exec, exec, s[4:5]
	s_getpc_b64 s[98:99]
	v_lshlrev_b32_e32 v250, 4, v158
	v_mov_b32_e32 v251, 0
	v_lshl_add_u64 v[250:251], s[98:99], 0, v[250:251]
	v_and_b32_e32 v250, -16, v250
	global_load_dwordx4 v[252:255], v[250:251], off
	v_lshl_add_u64 v[250:251], 64, 7, v[250:251]
	global_load_dwordx4 v[252:255], v[250:251], off
	v_lshl_add_u64 v[250:251], 64, 7, v[250:251]
	global_load_dwordx4 v[252:255], v[250:251], off
	v_lshl_add_u64 v[250:251], 64, 7, v[250:251]
	global_load_dwordx4 v[252:255], v[250:251], off
	s_mov_b64 s[0:1], s[80:81]
	v_mov_b32_e32 v2, v158
	s_waitcnt lgkmcnt(0)
	s_barrier
	s_getpc_b64 s[98:99]
	v_lshlrev_b32_e32 v250, 4, v158
	v_mov_b32_e32 v251, 0
	v_lshl_add_u64 v[250:251], s[98:99], 0, v[250:251]
	v_and_b32_e32 v250, -16, v250
	global_load_dwordx4 v[252:255], v[250:251], off
	v_lshl_add_u64 v[250:251], 64, 7, v[250:251]
	global_load_dwordx4 v[252:255], v[250:251], off
	v_lshl_add_u64 v[250:251], 64, 7, v[250:251]
	global_load_dwordx4 v[252:255], v[250:251], off
	v_lshl_add_u64 v[250:251], 64, 7, v[250:251]
	global_load_dwordx4 v[252:255], v[250:251], off
	s_load_dwordx2 s[10:11], s[0:1], 0xd8
	v_bfe_u32 v0, v2, 6, 2
	v_and_b32_e32 v1, 15, v2
	v_bfe_u32 v3, v2, 4, 2
	v_lshlrev_b32_e32 v152, 6, v0
	s_waitcnt lgkmcnt(0)
	s_add_u32 s14, s10, 0x1c00000
	s_addc_u32 s15, s11, 0
	s_add_u32 s16, s10, 0x400000
	s_addc_u32 s17, s11, 0
	s_add_u32 s1, s10, 0x5c00000
	s_addc_u32 s2, s11, 0
	s_cmpk_lg_i32 s76, 0x100
	s_cselect_b64 s[4:5], -1, 0
	v_writelane_b32 v222, s4, 3
	v_ashrrev_i32_e32 v4, 1, v2
	v_mov_b32_e32 v129, 0
	v_writelane_b32 v222, s5, 4
	s_and_b64 s[4:5], s[4:5], exec
	v_readlane_b32 s4, v222, 0
	s_cselect_b32 s46, s4, 0
	s_and_b32 s0, s28, 56
	s_bfe_u32 s3, s4, 0x30003
	v_writelane_b32 v222, s28, 5
	s_or_b32 s0, s3, s0
	v_writelane_b32 v222, s0, 6
	s_lshr_b32 s0, s4, 6
	v_writelane_b32 v222, s0, 7
	v_cmp_gt_u32_e64 s[4:5], 2, v0
	s_movk_i32 s0, 0xff80
	v_lshlrev_b32_e32 v0, 7, v0
	v_and_or_b32 v153, v4, s0, v1
	v_lshl_or_b32 v4, v3, 3, v0
	v_lshlrev_b32_e32 v0, 1, v2
	v_and_b32_e32 v128, 32, v0
	v_lshl_add_u64 v[0:1], s[10:11], 0, v[128:129]
	s_mov_b64 s[6:7], 0x34000
	s_movk_i32 s3, 0x210
	v_lshl_add_u64 v[130:131], v[0:1], 0, s[6:7]
	v_lshlrev_b32_e32 v0, 13, v3
	v_mul_lo_u32 v1, v153, s3
	s_add_u32 s18, s10, 0xf800000
	v_cmp_gt_u32_e64 s[6:7], 2, v3
	v_bfe_u32 v154, v2, 6, 1
	s_addc_u32 s19, s11, 0
	s_movk_i32 s50, 0x3f0
	s_movk_i32 s51, 0xf000
	s_mov_b64 s[20:21], 0x4000
	s_mov_b64 s[22:23], 0x8000
	s_mov_b64 s[24:25], 0xc000
	s_mov_b32 s52, 0x10000
	s_mov_b64 s[26:27], 0x1c00080
	s_mov_b64 s[28:29], 0x400080
	s_mov_b64 s[30:31], 0x1c04080
	s_mov_b64 s[34:35], 0x404080
	s_mov_b64 s[36:37], 0x1c08080
	s_mov_b64 s[38:39], 0x408080
	s_mov_b64 s[40:41], 0x1c0c080
	s_mov_b64 s[42:43], 0x40c080
	s_movk_i32 s53, 0x127f
	s_movk_i32 s54, 0x1280
	s_movk_i32 s55, 0x1180
	s_movk_i32 s56, 0x7fff
	v_lshlrev_b32_e32 v132, 1, v0
	s_movk_i32 s57, 0x1000
	s_movk_i32 s58, 0x2000
	s_movk_i32 s59, 0x3000
	s_mov_b32 s60, 0x11000
	s_mov_b32 s61, 0x12000
	s_mov_b32 s62, 0x13000
	s_mov_b32 s63, 0x20000
	s_mov_b32 s64, 0x21000
	s_mov_b32 s65, 0x22000
	s_mov_b32 s66, 0x23000
	s_mov_b32 s67, 0x30000
	s_mov_b32 s68, 0x31000
	s_mov_b32 s69, 0x32000
	s_mov_b32 s70, 0x33000
	s_movk_i32 s71, 0x1380
	s_movk_i32 s72, 0x2700
	v_mbcnt_hi_u32_b32 v159, -1, v30
	v_mov_b32_e32 v155, 0x3e38aa3b
	v_add_u32_e32 v156, v4, v1
	v_mov_b32_e32 v157, 0xffffff80
	v_writelane_b32 v222, s46, 8
	s_branch .LBB0_291

; __device__ __forceinline__ float bf2f(bf16_t h) { return __uint_as_float(((unsigned)h) << 16); }
; __device__ __forceinline__ int vblk() { return (int)blockIdx.x * 2 + half_id(); }
; __device__ __forceinline__ int vgrid() { return (int)gridDim.x * 2; }
; #define PF fresh_params()
; __device__ __forceinline__ void gla_prep(const Params& p, int tok0, int h, char* lds) {
;     const int tid = TIDX;
;     float* bc = (float*)lds;
;     float* lrs = (float*)(lds + 32768);
;     const bf16_t* Z = (const bf16_t*)(p.ws + OFF_Z);
;     for (int i = tid; i < 1024; i += NTHREADS) { const int t = i >> 4, rr = i & 15; lrs[i] = bf2f(Z[(size_t)(tok0 + t) * ZC + ZLR + rr]); }
; __device__ __forceinline__ void xcd_barrier(const XcdBarrier& b) {
;     ...
;     __syncthreads();
; __global__ void __launch_bounds__(BLOCK_THREADS, 2) mega(Params p_unused) {
;     ...
;     for (int task = vblk(); task < 1024; task += vgrid()) phaseG1_task(PF, task, hl);
.LBB0_376:
	s_or_b64 exec, exec, s[4:5]
	s_getpc_b64 s[98:99]
	v_lshlrev_b32_e32 v250, 4, v158
	v_mov_b32_e32 v251, 0
	v_lshl_add_u64 v[250:251], s[98:99], 0, v[250:251]
	v_and_b32_e32 v250, -16, v250
	global_load_dwordx4 v[252:255], v[250:251], off
	v_lshl_add_u64 v[250:251], 64, 7, v[250:251]
	global_load_dwordx4 v[252:255], v[250:251], off
	v_lshl_add_u64 v[250:251], 64, 7, v[250:251]
	global_load_dwordx4 v[252:255], v[250:251], off
	v_lshl_add_u64 v[250:251], 64, 7, v[250:251]
	global_load_dwordx4 v[252:255], v[250:251], off
	v_readfirstlane_b32 s0, v158
	s_lshr_b32 s4, s0, 8
	s_add_i32 s14, s4, s85
	s_cmpk_gt_i32 s14, 0x3ff
	s_waitcnt lgkmcnt(0)
	s_barrier
	s_getpc_b64 s[98:99]
	v_lshlrev_b32_e32 v250, 4, v158
	v_mov_b32_e32 v251, 0
	v_lshl_add_u64 v[250:251], s[98:99], 0, v[250:251]
	v_and_b32_e32 v250, -16, v250
	global_load_dwordx4 v[252:255], v[250:251], off
	v_lshl_add_u64 v[250:251], 64, 7, v[250:251]
	global_load_dwordx4 v[252:255], v[250:251], off
	v_lshl_add_u64 v[250:251], 64, 7, v[250:251]
	global_load_dwordx4 v[252:255], v[250:251], off
	v_lshl_add_u64 v[250:251], 64, 7, v[250:251]
	global_load_dwordx4 v[252:255], v[250:251], off
	s_cbranch_scc1 .LBB0_387
	v_readlane_b32 s5, v222, 0
	s_lshl_b32 s2, s5, 5
	s_lshl_b32 s3, s4, 4
	s_lshl_b32 s5, s5, 7
	s_lshl_b32 s4, s4, 6
	s_lshl_b32 s0, s76, 1
	s_add_i32 s1, s33, 0x8000
	s_add_i32 s2, s2, s3
	s_lshl_b32 s3, s76, 5
	s_add_i32 s36, s5, s4
	s_lshl_b32 s37, s76, 7
	v_mov_b32_e32 v9, 0
	s_mov_b64 s[16:17], 0x5c02660
	s_movk_i32 s38, 0x2700
	s_movk_i32 s39, 0x2ff
	s_movk_i32 s40, 0x7f
	s_mov_b32 s19, 0
	s_mov_b32 s41, 0xbfb8aa3b
	s_mov_b32 s42, 0x800000
	s_mov_b32 s43, 0x3f317217
	s_mov_b32 s44, 0x7f800000
	v_mov_b32_e32 v20, 0x41b17218
	s_movk_i32 s45, 0x80
	s_mov_b64 s[20:21], 0x5c00000
	s_movk_i32 s46, 0x7fff
	s_mov_b64 s[22:23], 0x60
	s_mov_b64 s[24:25], 0x80
	s_mov_b64 s[26:27], 0xa0
	s_mov_b64 s[28:29], 0xc0
	s_mov_b64 s[30:31], 0xe0
	s_branch .LBB0_379

; __device__ __forceinline__ int vblk() { return (int)blockIdx.x * 2 + half_id(); }
; __device__ __forceinline__ int vgrid() { return (int)gridDim.x * 2; }
; __device__ void phaseG2(const Params& p) {
;     bf16_t* L = (bf16_t*)p.out;
;     const float* dec = (const float*)(p.ws + OFF_DEC);
;     for (int idx = vblk() * NTHREADS + (int)(threadIdx.x & 255); idx < 32 * 256 * 16; idx += vgrid() * NTHREADS) {
;         const int d8 = idx & 15, e = (idx >> 4) & 255, bh = idx >> 12;
;         float st[8];
; __device__ __forceinline__ void xcd_barrier(const XcdBarrier& b) {
;     ...
;     __syncthreads();
.LBB0_448:
	s_or_b64 exec, exec, s[4:5]
	s_getpc_b64 s[98:99]
	v_lshlrev_b32_e32 v250, 4, v158
	v_mov_b32_e32 v251, 0
	v_lshl_add_u64 v[250:251], s[98:99], 0, v[250:251]
	v_and_b32_e32 v250, -16, v250
	global_load_dwordx4 v[252:255], v[250:251], off
	v_lshl_add_u64 v[250:251], 64, 7, v[250:251]
	global_load_dwordx4 v[252:255], v[250:251], off
	v_lshl_add_u64 v[250:251], 64, 7, v[250:251]
	global_load_dwordx4 v[252:255], v[250:251], off
	v_lshl_add_u64 v[250:251], 64, 7, v[250:251]
	global_load_dwordx4 v[252:255], v[250:251], off
	v_readfirstlane_b32 s0, v158
	v_readlane_b32 s1, v222, 0
	s_and_b32 s0, s0, 0xffffff00
	s_lshl_b32 s1, s1, 9
	s_add_i32 s0, s0, s1
	v_or_b32_sdwa v12, s0, v158 dst_sel:DWORD dst_unused:UNUSED_PAD src0_sel:DWORD src1_sel:BYTE_0
	s_mov_b32 s0, 0x20000
	s_mov_b64 s[10:11], s[80:81]
	v_cmp_gt_i32_e32 vcc, s0, v12
	s_waitcnt lgkmcnt(0)
	s_barrier
	s_getpc_b64 s[98:99]
	v_lshlrev_b32_e32 v250, 4, v158
	v_mov_b32_e32 v251, 0
	v_lshl_add_u64 v[250:251], s[98:99], 0, v[250:251]
	v_and_b32_e32 v250, -16, v250
	global_load_dwordx4 v[252:255], v[250:251], off
	v_lshl_add_u64 v[250:251], 64, 7, v[250:251]
	global_load_dwordx4 v[252:255], v[250:251], off
	v_lshl_add_u64 v[250:251], 64, 7, v[250:251]
	global_load_dwordx4 v[252:255], v[250:251], off
	v_lshl_add_u64 v[250:251], 64, 7, v[250:251]
	global_load_dwordx4 v[252:255], v[250:251], off
	s_and_saveexec_b64 s[8:9], vcc
	s_cbranch_execz .LBB0_453
	s_load_dwordx4 s[4:7], s[10:11], 0xd0
	s_lshl_b32 s0, s76, 9
	v_lshlrev_b32_e32 v13, 3, v12
	s_lshl_b32 s1, s76, 12
	s_mov_b64 s[10:11], 0
	s_movk_i32 s2, 0x1e0
	s_mov_b64 s[14:15], 0x1b4000
	s_mov_b32 s3, 0x1b4000
	s_mov_b32 s22, 0x10000
	s_mov_b64 s[16:17], 0x1b4200
	s_mov_b64 s[18:19], 0x20000
	s_mov_b32 s23, 0x1ffff

; __device__ __forceinline__ int half_id() { return __builtin_amdgcn_readfirstlane((int)(threadIdx.x >> 8)); }
; __device__ __forceinline__ int vblk() { return (int)blockIdx.x * 2 + half_id(); }
; __device__ __forceinline__ int vgrid() { return (int)gridDim.x * 2; }
; #define PF fresh_params()
; __device__ void phaseN2_task(const Params& p, int task, char* lds, bf16_t* ydst, int ystride, volatile unsigned* uex, char* ldsb) {
;     const int tid = TIDX, lane = tid & 63, wave = tid >> 6, r = lane & 15, q = lane >> 4;
;     const int t512 = tid + half_id() * 256;
;     const int pair = task >> 1, g = pair & 1, b = (pair >> 1) & 7;
;     const int hi_ = pair >> 4, kq_ = hi_ >> 4, aa_ = hi_ & 15;
;     const int tpi_ = kq_ == 0 ? 63 - aa_ : (kq_ == 1 ? 32 + aa_ : (kq_ == 2 ? 31 - aa_ : aa_));
;     const int tt = tpi_ * 2 + (task & 1);
;     const int t0 = tt * 16, t = t0 + r;
;     const int cur = t0 >> 6;
;     bf16_t* Z = (bf16_t*)(p.ws + OFF_Z);
;     const size_t rowb = (size_t)b * SEQ;
;     bf16_t* Kc = (bf16_t*)ldsb;
;     bf16_t* VcT = (bf16_t*)(ldsb + 18432);
;     bf16_t* Ks = (bf16_t*)ldsb;
;     bf16_t* VT = (bf16_t*)(ldsb + 18432);
;     float* impw = (float*)(lds + 35840);
;     float* scs = (float*)(lds + 35840 + 32768);
;     unsigned* selm = (unsigned*)(lds + 35840 + 32768 + 2048);
; __device__ __forceinline__ void xcd_barrier(const XcdBarrier& b) {
;     ...
;     __syncthreads();
; __global__ void __launch_bounds__(BLOCK_THREADS, 2) mega(Params p_unused) {
;     ...
;     for (int task = vblk(); task < 2048; task += vgrid()) phaseN2_task(PF, task, hl, (bf16_t*)(PF.ws + OFF_Z) + ZQ_N, ZC, uex, lds);
.LBB0_591:
	v_writelane_b32 v222, s84, 9
	v_writelane_b32 v222, s83, 10
	s_or_b64 exec, exec, s[4:5]
	s_getpc_b64 s[98:99]
	v_lshlrev_b32_e32 v250, 4, v158
	v_mov_b32_e32 v251, 0
	v_lshl_add_u64 v[250:251], s[98:99], 0, v[250:251]
	v_and_b32_e32 v250, -16, v250
	global_load_dwordx4 v[252:255], v[250:251], off
	v_lshl_add_u64 v[250:251], 64, 7, v[250:251]
	global_load_dwordx4 v[252:255], v[250:251], off
	v_lshl_add_u64 v[250:251], 64, 7, v[250:251]
	global_load_dwordx4 v[252:255], v[250:251], off
	v_lshl_add_u64 v[250:251], 64, 7, v[250:251]
	global_load_dwordx4 v[252:255], v[250:251], off
	v_readfirstlane_b32 s0, v158
	s_lshr_b32 s0, s0, 8
	s_add_i32 s95, s0, s85
	s_cmpk_gt_i32 s95, 0x7ff
	s_waitcnt lgkmcnt(0)
	s_barrier
	s_getpc_b64 s[98:99]
	v_lshlrev_b32_e32 v250, 4, v158
	v_mov_b32_e32 v251, 0
	v_lshl_add_u64 v[250:251], s[98:99], 0, v[250:251]
	v_and_b32_e32 v250, -16, v250
	global_load_dwordx4 v[252:255], v[250:251], off
	v_lshl_add_u64 v[250:251], 64, 7, v[250:251]
	global_load_dwordx4 v[252:255], v[250:251], off
	v_lshl_add_u64 v[250:251], 64, 7, v[250:251]
	global_load_dwordx4 v[252:255], v[250:251], off
	v_lshl_add_u64 v[250:251], 64, 7, v[250:251]
	global_load_dwordx4 v[252:255], v[250:251], off
	v_writelane_b32 v222, s85, 11
	s_cbranch_scc1 .LBB0_632
	s_add_i32 s0, s33, 0x11430
	v_writelane_b32 v222, s0, 12
	s_add_i32 s0, s33, 0x11420
	v_writelane_b32 v222, s0, 13
	s_add_i32 s0, s33, 0x11410
	v_writelane_b32 v222, s0, 14
	s_load_dwordx2 s[0:1], s[80:81], 0xe0
	s_mov_b64 s[2:3], src_shared_base
	s_waitcnt lgkmcnt(0)
	s_mov_b32 s1, s3
	s_add_i32 s82, s33, 0x10c00
	s_add_i32 s72, s33, 0x11400
	s_lshl_b32 s77, s0, 1
	s_add_i32 s0, s33, 0x8c00
	v_writelane_b32 v222, s0, 15
	s_add_i32 s0, s33, 0x9c00
	v_writelane_b32 v222, s0, 16
	s_movk_i32 s97, 0x2700
	s_mov_b32 s85, 0
	v_mov_b32_e32 v89, 0
	s_movk_i32 s94, 0x90
	s_movk_i32 s73, 0x110
	v_mov_b32_e32 v118, 0xf149f2ca
	v_mov_b32_e32 v119, 0x7e
	v_mov_b32_e32 v120, 0x49742400
	v_mov_b32_e32 v90, 0x24020
	v_writelane_b32 v222, s0, 17
	v_mov_b32_e32 v91, s3
	v_mov_b32_e32 v92, 0x24024
	v_mov_b32_e32 v121, 0x2400
	v_mov_b32_e32 v122, 0x2200
	v_mov_b32_e32 v123, 0xff61b1e6
	v_writelane_b32 v222, s1, 18
	s_branch .LBB0_594

; __device__ __forceinline__ int launder_i(int x) { asm volatile("" : "+v"(x)); return x; }
; #define TIDX512 launder_i((int)threadIdx.x)
; __device__ __forceinline__ void gemm_prologue(const GemmSrc& g, char* lds) { gemm_issue(g, 0, 0, lds); }
; __device__ void phaseM1(const Params& p, char* lds) {
;     const int tid_ = TIDX512; const int lane = tid_ & 63, wave = tid_ >> 6;
;     const int wr = wave >> 2, wc = wave & 3, r = lane & 15, q = lane >> 4;
;     const bf16_t* H = (const bf16_t*)(p.ws + OFF_H);
;     const bf16_t* Z = (const bf16_t*)(p.ws + OFF_Z);
;     bf16_t* M = (bf16_t*)(p.ws + OFF_M);
;     u32x4* SG = (u32x4*)p.out;
;     u32x4* PA = (u32x4*)((char*)p.out + 33554432);
;     TileIter tit(4, lds);
;     int bm, bn;
;     while (tit.next(bm, bn)) {
;         const int m0 = bm * 256, n0 = bn * 256;
;         const int pbase = launder_i(((bm * 4 + bn) * 16) * 512 + tid_);
;         GemmSrc g = gemm_src(H, DM, (const bf16_t*)(p.ws + OFF_WM), DM, m0, n0);
;         gemm_prologue(g, lds);
; __device__ __forceinline__ void xcd_barrier(const XcdBarrier& b) {
;     ...
;     __syncthreads();
.LBB0_700:
	s_or_b64 exec, exec, s[4:5]
	s_getpc_b64 s[98:99]
	v_lshlrev_b32_e32 v250, 4, v158
	v_mov_b32_e32 v251, 0
	v_lshl_add_u64 v[250:251], s[98:99], 0, v[250:251]
	v_and_b32_e32 v250, -16, v250
	global_load_dwordx4 v[252:255], v[250:251], off
	v_lshl_add_u64 v[250:251], 64, 7, v[250:251]
	global_load_dwordx4 v[252:255], v[250:251], off
	v_lshl_add_u64 v[250:251], 64, 7, v[250:251]
	global_load_dwordx4 v[252:255], v[250:251], off
	v_lshl_add_u64 v[250:251], 64, 7, v[250:251]
	global_load_dwordx4 v[252:255], v[250:251], off
	s_mov_b64 s[0:1], s[80:81]
	v_mov_b32_e32 v144, v158
	s_waitcnt lgkmcnt(0)
	s_barrier
	s_getpc_b64 s[98:99]
	v_lshlrev_b32_e32 v250, 4, v158
	v_mov_b32_e32 v251, 0
	v_lshl_add_u64 v[250:251], s[98:99], 0, v[250:251]
	v_and_b32_e32 v250, -16, v250
	global_load_dwordx4 v[252:255], v[250:251], off
	v_lshl_add_u64 v[250:251], 64, 7, v[250:251]
	global_load_dwordx4 v[252:255], v[250:251], off
	v_lshl_add_u64 v[250:251], 64, 7, v[250:251]
	global_load_dwordx4 v[252:255], v[250:251], off
	v_lshl_add_u64 v[250:251], 64, 7, v[250:251]
	global_load_dwordx4 v[252:255], v[250:251], off
	s_load_dwordx4 s[4:7], s[0:1], 0xd0
	v_and_b32_e32 v0, 15, v144
	v_lshrrev_b32_e32 v1, 1, v144
	s_mov_b32 s0, 0xfffff80
	v_lshlrev_b32_e32 v2, 1, v144
	s_waitcnt lgkmcnt(0)
	s_add_u32 s8, s6, 0x1c00000
	s_addc_u32 s9, s7, 0
	s_add_u32 s58, s6, 0x5c00000
	s_addc_u32 s59, s7, 0
	s_add_u32 s60, s6, 0x3c00000
	s_addc_u32 s61, s7, 0
	s_add_u32 s10, s4, 0x2000000
	s_addc_u32 s11, s5, 0
	s_add_u32 s12, s6, 0xdc0000
	v_and_or_b32 v0, v1, s0, v0
	v_and_b32_e32 v2, 0x180, v2
	s_movk_i32 s62, 0x210
	s_addc_u32 s13, s7, 0
	v_and_or_b32 v1, v1, 24, v2
	v_mul_lo_u32 v0, v0, s62
	s_add_u32 s14, s6, 0xfc0000
	s_addc_u32 s15, s7, 0
	s_movk_i32 s63, 0xffe0
	v_mov_b32_e32 v129, 0
	s_movk_i32 s64, 0x3f0
	s_movk_i32 s65, 0xf000
	s_mov_b64 s[16:17], 0x4000
	s_movk_i32 s66, 0x400
	s_mov_b64 s[18:19], 0x8000
	s_mov_b64 s[20:21], 0xc000
	s_movk_i32 s67, 0x1800
	s_mov_b64 s[22:23], 0x80
	s_mov_b32 s68, 0x10000
	s_mov_b64 s[24:25], 0x4080
	s_mov_b64 s[26:27], 0x8080
	s_mov_b64 s[28:29], 0xc080
	s_mov_b32 s31, 0
	s_mov_b32 s69, 0x11c0000
	s_movk_i32 s70, 0x2700
	s_mov_b64 s[34:35], 0x13800
	s_mov_b64 s[36:37], 0x27000
	s_mov_b64 s[38:39], 0x3a800
	s_mov_b64 s[40:41], 0x5c00080
	s_mov_b64 s[42:43], 0x5c13880
	s_mov_b64 s[44:45], 0x5c27080
	s_mov_b64 s[46:47], 0x5c3a880
	v_add_u32_e32 v145, v1, v0
	v_readlane_b32 s71, v222, 8
	s_branch .LBB0_703

; #define TIDX512 launder_i((int)threadIdx.x)
; __device__ void phaseM2(const Params& p, char* lds) {
;     const int tid_ = TIDX512; const int lane = tid_ & 63, wave = tid_ >> 6;
;     const int wr = wave >> 2, wc = wave & 3, r = lane & 15, q = lane >> 4;
;     const bf16_t* M = (const bf16_t*)(p.ws + OFF_M);
;     const float* mod = (const float*)(p.ws + OFF_MOD);
;     TileIter tit(4, lds);
;     int bm, bn;
;     while (tit.next(bm, bn)) {
;         const int m0 = bm * 256, n0 = bn * 256;
;         f32x4 acc[8][4];
;         zero_acc(acc);
;         gemm_core(acc, M, DM, (const bf16_t*)(p.ws + OFF_WO), DM, DM, m0, n0, lds);
; __device__ __forceinline__ void xcd_barrier(const XcdBarrier& b) {
;     ...
;     __syncthreads();
.LBB0_774:
	s_or_b64 exec, exec, s[4:5]
	s_getpc_b64 s[98:99]
	v_lshlrev_b32_e32 v250, 4, v158
	v_mov_b32_e32 v251, 0
	v_lshl_add_u64 v[250:251], s[98:99], 0, v[250:251]
	v_and_b32_e32 v250, -16, v250
	global_load_dwordx4 v[252:255], v[250:251], off
	v_lshl_add_u64 v[250:251], 64, 7, v[250:251]
	global_load_dwordx4 v[252:255], v[250:251], off
	v_lshl_add_u64 v[250:251], 64, 7, v[250:251]
	global_load_dwordx4 v[252:255], v[250:251], off
	v_lshl_add_u64 v[250:251], 64, 7, v[250:251]
	global_load_dwordx4 v[252:255], v[250:251], off
	s_mov_b64 s[8:9], s[80:81]
	s_waitcnt lgkmcnt(0)
	v_mov_b32_e32 v0, v158
	s_barrier
	s_getpc_b64 s[98:99]
	v_lshlrev_b32_e32 v250, 4, v158
	v_mov_b32_e32 v251, 0
	v_lshl_add_u64 v[250:251], s[98:99], 0, v[250:251]
	v_and_b32_e32 v250, -16, v250
	global_load_dwordx4 v[252:255], v[250:251], off
	v_lshl_add_u64 v[250:251], 64, 7, v[250:251]
	global_load_dwordx4 v[252:255], v[250:251], off
	v_lshl_add_u64 v[250:251], 64, 7, v[250:251]
	global_load_dwordx4 v[252:255], v[250:251], off
	v_lshl_add_u64 v[250:251], 64, 7, v[250:251]
	global_load_dwordx4 v[252:255], v[250:251], off
	s_load_dwordx2 s[6:7], s[8:9], 0xd8
	v_bfe_u32 v1, v0, 6, 2
	v_and_b32_e32 v160, 15, v0
	v_bfe_u32 v2, v0, 4, 2
	v_ashrrev_i32_e32 v0, 1, v0
	s_waitcnt lgkmcnt(0)
	s_add_u32 s4, s6, 0x3c00000
	s_addc_u32 s5, s7, 0
	v_and_b32_e32 v161, 0xffffff80, v0
	v_lshlrev_b32_e32 v0, 2, v2
	s_add_u32 s10, s6, 0x15c0000
	v_lshl_or_b32 v162, v1, 6, v0
	v_lshlrev_b32_e32 v0, 7, v1
	v_or_b32_e32 v1, v161, v160
	s_movk_i32 s0, 0x210
	s_addc_u32 s11, s7, 0
	v_lshl_or_b32 v0, v2, 3, v0
	v_mul_lo_u32 v1, v1, s0
	s_add_u32 s1, s6, 0xbd00000
	s_addc_u32 s2, s7, 0
	v_mov_b32_e32 v153, 0
	s_movk_i32 s3, 0x3f0
	s_movk_i32 s42, 0xf000
	s_mov_b64 s[12:13], 0x4000
	s_movk_i32 s43, 0x400
	s_mov_b64 s[14:15], 0x8000
	s_mov_b64 s[16:17], 0xc000
	s_mov_b32 s44, 0x10000
	s_mov_b64 s[18:19], 0x3c00080
	s_mov_b64 s[20:21], 0x15c0080
	s_mov_b64 s[22:23], 0x3c04080
	s_mov_b64 s[24:25], 0x15c4080
	s_mov_b64 s[26:27], 0x3c08080
	s_mov_b64 s[28:29], 0x15c8080
	s_mov_b64 s[30:31], 0x3c0c080
	s_mov_b64 s[34:35], 0x15cc080
	s_mov_b64 s[36:37], 0x6000
	v_add_u32_e32 v163, v0, v1
	s_mov_b32 s45, s50
	s_branch .LBB0_777

; __device__ __forceinline__ float bf_lo(unsigned u) { return __uint_as_float(u << 16); }
; __device__ __forceinline__ float bf_hi(unsigned u) { return __uint_as_float(u & 0xffff0000u); }
; __device__ __forceinline__ int vblk() { return (int)blockIdx.x * 2 + half_id(); }
; __device__ __forceinline__ int vgrid() { return (int)gridDim.x * 2; }
; __device__ void phase_modnorm(const Params& p, const float* __restrict__ src, const bf16_t* __restrict__ srcb, const float* __restrict__ g, int shift_idx, int scale_idx, bf16_t* __restrict__ dst) {
;     const int tid_ = TIDX; const int lane = tid_ & 63, wave = tid_ >> 6;
;     const float* mod = (const float*)(p.ws + OFF_MOD);
;     for (int tok = vblk() * 4 + wave; tok < NTOK; tok += vgrid() * 4) {
;         const int b = tok >> 11;
;         const float* xr = src + (size_t)tok * DM;
;         f32x4 v[4];
;         float ss = 0.f;
; #pragma unroll
;         for (int c = 0; c < 4; c++) {
;             if (srcb) {
;                 const u32x2 w = *(const u32x2*)(srcb + (size_t)tok * DM + c * 256 + lane * 4);
;                 v[c] = (f32x4){bf_lo(w.x), bf_hi(w.x), bf_lo(w.y), bf_hi(w.y)};
;             } else v[c] = *(const f32x4*)(xr + c * 256 + lane * 4);
;             ss += v[c][0] * v[c][0] + v[c][1] * v[c][1] + v[c][2] * v[c][2] + v[c][3] * v[c][3];
;         }
;         ss = wave_sum(ss);
;         const float rstd = rsqrtf(ss * (1.f / 1024.f) + 1e-6f);
; __device__ __forceinline__ void xcd_barrier(const XcdBarrier& b) {
;     ...
;     __syncthreads();
.LBB0_852:
	s_or_b64 exec, exec, s[4:5]
	s_getpc_b64 s[98:99]
	v_lshlrev_b32_e32 v250, 4, v158
	v_mov_b32_e32 v251, 0
	v_lshl_add_u64 v[250:251], s[98:99], 0, v[250:251]
	v_and_b32_e32 v250, -16, v250
	global_load_dwordx4 v[252:255], v[250:251], off
	v_lshl_add_u64 v[250:251], 64, 7, v[250:251]
	global_load_dwordx4 v[252:255], v[250:251], off
	v_lshl_add_u64 v[250:251], 64, 7, v[250:251]
	global_load_dwordx4 v[252:255], v[250:251], off
	v_readfirstlane_b32 s0, v158
	s_lshr_b32 s0, s0, 6
	s_mov_b64 s[6:7], s[80:81]
	v_mov_b32_e32 v18, v158
	s_and_b32 s0, s0, 0x3fffffc
	s_waitcnt lgkmcnt(0)
	s_barrier
	s_getpc_b64 s[98:99]
	v_lshlrev_b32_e32 v250, 4, v158
	v_mov_b32_e32 v251, 0
	v_lshl_add_u64 v[250:251], s[98:99], 0, v[250:251]
	v_and_b32_e32 v250, -16, v250
	global_load_dwordx4 v[252:255], v[250:251], off
	v_lshl_add_u64 v[250:251], 64, 7, v[250:251]
	global_load_dwordx4 v[252:255], v[250:251], off
	v_lshl_add_u64 v[250:251], 64, 7, v[250:251]
	global_load_dwordx4 v[252:255], v[250:251], off
	s_add_i32 s0, s0, s28
	v_lshrrev_b32_e32 v0, 6, v18
	v_and_or_b32 v16, v0, 3, s0
	s_movk_i32 s0, 0x4000
	v_cmp_gt_i32_e32 vcc, s0, v16
	s_and_saveexec_b64 s[4:5], vcc
	s_cbranch_execz .LBB0_855
	s_load_dwordx2 s[0:1], s[6:7], 0x30
	v_lshlrev_b32_e32 v0, 2, v18
	v_and_b32_e32 v22, 0xfc, v0
	v_lshlrev_b32_e32 v17, 2, v22
	v_xor_b32_e32 v20, 32, v159
	s_waitcnt lgkmcnt(0)
	global_load_dwordx4 v[0:3], v17, s[0:1]
	global_load_dwordx4 v[4:7], v17, s[0:1] offset:1024
	global_load_dwordx4 v[8:11], v17, s[0:1] offset:2048
	global_load_dwordx4 v[12:15], v17, s[0:1] offset:3072
	v_and_b32_e32 v17, 64, v159
	v_add_u32_e32 v17, 64, v17
	v_cmp_lt_i32_e32 vcc, v20, v17
	s_load_dwordx2 s[0:1], s[6:7], 0xd8
	v_mov_b32_e32 v19, 0
	v_cndmask_b32_e32 v20, v159, v20, vcc
	v_lshlrev_b32_e32 v28, 2, v20
	v_xor_b32_e32 v20, 16, v159
	v_cmp_lt_i32_e32 vcc, v20, v17
	s_waitcnt lgkmcnt(0)
	s_add_u32 s8, s0, 0x4000
	s_addc_u32 s9, s1, 0
	v_cndmask_b32_e32 v20, v159, v20, vcc
	v_lshlrev_b32_e32 v29, 2, v20
	v_xor_b32_e32 v20, 8, v159
	v_cmp_lt_i32_e32 vcc, v20, v17
	s_lshl_b32 s10, s72, 3
	v_or_b32_e32 v24, 0x100, v22
	v_cndmask_b32_e32 v20, v159, v20, vcc
	v_lshlrev_b32_e32 v30, 2, v20
	v_xor_b32_e32 v20, 4, v159
	v_cmp_lt_i32_e32 vcc, v20, v17
	v_or_b32_e32 v26, 0x200, v22
	v_or_b32_e32 v34, 0x300, v22
	v_cndmask_b32_e32 v20, v159, v20, vcc
	v_lshlrev_b32_e32 v31, 2, v20
	v_xor_b32_e32 v20, 2, v159
	v_cmp_lt_i32_e32 vcc, v20, v17
	s_ashr_i32 s11, s10, 31
	s_mov_b64 s[6:7], 0x4000
	v_cndmask_b32_e32 v20, v159, v20, vcc
	v_lshlrev_b32_e32 v32, 2, v20
	v_xor_b32_e32 v20, 1, v159
	v_cmp_lt_i32_e32 vcc, v20, v17
	s_lshl_b64 s[12:13], s[10:11], 11
	s_mov_b64 s[14:15], 0
	v_cndmask_b32_e32 v17, v159, v20, vcc
	v_lshlrev_b32_e32 v33, 2, v17
	v_ashrrev_i32_e32 v17, 31, v16
	v_lshlrev_b64 v[20:21], 11, v[16:17]
	v_and_b32_e32 v17, 63, v18
	v_lshl_or_b32 v20, v17, 3, v20
	v_lshl_add_u64 v[20:21], s[0:1], 0, v[20:21]
	s_mov_b64 s[0:1], 0xbd00000
	v_lshl_add_u64 v[20:21], v[20:21], 0, s[0:1]
	s_mov_b64 s[16:17], 0x3000
	v_lshlrev_b32_e32 v18, 2, v22
	v_lshlrev_b32_e32 v22, 2, v24
	v_mov_b32_e32 v23, v19
	v_lshlrev_b32_e32 v24, 2, v26
	v_mov_b32_e32 v25, v19
	v_lshlrev_b32_e32 v26, 2, v34
	v_mov_b32_e32 v27, v19
	v_mov_b32_e32 v17, 0x358637bd
	s_mov_b32 s0, 0x800000
	s_mov_b32 s1, 0xf5f00000
	s_mov_b32 s2, 0xf5f01000
	s_movk_i32 s3, 0x3fff

; #define TIDX512 launder_i((int)threadIdx.x)
; __device__ void phaseP1(const Params& p, char* lds) {
;     const int tid_ = TIDX512; const int lane = tid_ & 63, wave = tid_ >> 6;
;     const int wr = wave >> 2, wc = wave & 3, r = lane & 15, q = lane >> 4;
;     const bf16_t* H = (const bf16_t*)(p.ws + OFF_H);
;     bf16_t* QP = (bf16_t*)(p.ws + OFF_QP);
;     TileIter tit(8, lds);
;     int bm, bn;
;     while (tit.next(bm, bn)) {
;         const int m0 = bm * 256, n0 = bn * 256;
;         f32x4 acc[8][4];
;         zero_acc(acc);
;         gemm_core(acc, H, DM, (const bf16_t*)(p.ws + OFF_WQ), DM, DM, m0, n0, lds);
; __device__ __forceinline__ void xcd_barrier(const XcdBarrier& b) {
;     ...
;     __syncthreads();
.LBB0_906:
	s_or_b64 exec, exec, s[4:5]
	s_getpc_b64 s[98:99]
	v_lshlrev_b32_e32 v250, 4, v158
	v_mov_b32_e32 v251, 0
	v_lshl_add_u64 v[250:251], s[98:99], 0, v[250:251]
	v_and_b32_e32 v250, -16, v250
	global_load_dwordx4 v[252:255], v[250:251], off
	v_lshl_add_u64 v[250:251], 64, 7, v[250:251]
	global_load_dwordx4 v[252:255], v[250:251], off
	s_mov_b64 s[0:1], s[80:81]
	s_waitcnt lgkmcnt(0)
	v_mov_b32_e32 v0, v158
	s_barrier
	s_getpc_b64 s[98:99]
	v_lshlrev_b32_e32 v250, 4, v158
	v_mov_b32_e32 v251, 0
	v_lshl_add_u64 v[250:251], s[98:99], 0, v[250:251]
	v_and_b32_e32 v250, -16, v250
	global_load_dwordx4 v[252:255], v[250:251], off
	v_lshl_add_u64 v[250:251], 64, 7, v[250:251]
	global_load_dwordx4 v[252:255], v[250:251], off
	s_load_dwordx2 s[4:5], s[0:1], 0xd8
	v_and_b32_e32 v1, 15, v0
	v_lshrrev_b32_e32 v2, 1, v0
	s_mov_b32 s2, 0xfffff80
	v_lshlrev_b32_e32 v0, 1, v0
	s_waitcnt lgkmcnt(0)
	s_add_u32 s6, s4, 0x1c00000
	s_addc_u32 s7, s5, 0
	s_add_u32 s0, s4, 0x5c00000
	s_addc_u32 s1, s5, 0
	v_and_or_b32 v1, v2, s2, v1
	v_and_b32_e32 v0, 0x180, v0
	s_movk_i32 s2, 0x210
	v_and_or_b32 v0, v2, 24, v0
	v_mul_lo_u32 v1, v1, s2
	s_add_u32 s8, s4, 0x17c0000
	s_addc_u32 s9, s5, 0
	v_mov_b32_e32 v129, 0
	s_movk_i32 s3, 0x3f0
	s_movk_i32 s38, 0xf000
	s_mov_b64 s[10:11], 0x4000
	s_mov_b64 s[12:13], 0x8000
	s_movk_i32 s39, 0x800
	s_mov_b64 s[14:15], 0xc000
	s_mov_b32 s40, 0x10000
	s_mov_b64 s[16:17], 0x1c00080
	s_mov_b64 s[18:19], 0x17c0080
	s_mov_b64 s[20:21], 0x1c04080
	s_mov_b64 s[22:23], 0x17c4080
	s_mov_b64 s[24:25], 0x1c08080
	s_mov_b64 s[26:27], 0x17c8080
	s_mov_b64 s[28:29], 0x1c0c080
	s_mov_b64 s[30:31], 0x17cc080
	v_add_u32_e32 v138, v0, v1
	s_branch .LBB0_909

; __device__ __forceinline__ int vblk() { return (int)blockIdx.x * 2 + half_id(); }
; __device__ __forceinline__ int vgrid() { return (int)gridDim.x * 2; }
; #define PF fresh_params()
; __device__ __forceinline__ void xcd_barrier(const XcdBarrier& b) {
;     ...
;     __syncthreads();
; __global__ void __launch_bounds__(BLOCK_THREADS, 2) mega(Params p_unused) {
;     ...
;     {
;         const int vg = vgrid(), gsz = (vg & 7) == 0 ? 4 : 1;
;         for (int t0 = vblk(); t0 < 2048; t0 += gsz * vg) {
;             const int rem = (2048 - t0 + vg - 1) / vg;
;             phaseP2_group(PF, t0, vg, rem < gsz ? rem : gsz, hl);
;         }
.LBB0_973:
	s_or_b64 exec, exec, s[4:5]
	s_getpc_b64 s[98:99]
	v_lshlrev_b32_e32 v250, 4, v158
	v_mov_b32_e32 v251, 0
	v_lshl_add_u64 v[250:251], s[98:99], 0, v[250:251]
	v_and_b32_e32 v250, -16, v250
	global_load_dwordx4 v[252:255], v[250:251], off
	v_lshl_add_u64 v[250:251], 64, 7, v[250:251]
	global_load_dwordx4 v[252:255], v[250:251], off
	v_readfirstlane_b32 s0, v158
	s_lshr_b32 s0, s0, 8
	s_add_i32 s0, s0, s77
	s_cmpk_gt_i32 s0, 0x7ff
	s_waitcnt lgkmcnt(0)
	s_barrier
	s_getpc_b64 s[98:99]
	v_lshlrev_b32_e32 v250, 4, v158
	v_mov_b32_e32 v251, 0
	v_lshl_add_u64 v[250:251], s[98:99], 0, v[250:251]
	v_and_b32_e32 v250, -16, v250
	global_load_dwordx4 v[252:255], v[250:251], off
	v_lshl_add_u64 v[250:251], 64, 7, v[250:251]
	global_load_dwordx4 v[252:255], v[250:251], off
	s_cbranch_scc1 .LBB0_989
	s_lshl_b32 s1, s72, 1
	s_and_b32 s3, s72, 3
	s_add_i32 s2, s1, 0x7ff
	s_cmp_eq_u32 s3, 0
	s_cselect_b32 s3, 4, 1
	s_cselect_b32 s4, 2, 0
	s_abs_i32 s24, s1
	v_cvt_f32_u32_e32 v0, s24
	s_lshl_b32 s27, s1, s4
	s_sub_i32 s4, 0, s24
	s_add_i32 s5, s0, s1
	v_rcp_iflag_f32_e32 v0, v0
	s_mov_b32 s9, 0
	s_bfe_i32 s25, s72, 0x1001e
	s_add_i32 s26, s33, 0x8000
	v_mul_f32_e32 v0, 0x4f7ffffe, v0
	v_cvt_u32_f32_e32 v0, v0
	s_lshl_b32 s29, s5, 3
	s_lshl_b32 s30, s27, 3
	s_lshl_b32 s31, s72, 4
	v_readfirstlane_b32 s6, v0
	s_mul_i32 s4, s4, s6
	s_mul_hi_u32 s4, s6, s4
	s_add_i32 s28, s6, s4
	s_movk_i32 s34, 0xffc0
	v_mov_b32_e32 v33, 0
	s_mov_b64 s[10:11], 0x234000
	s_movk_i32 s35, 0x7f
	s_movk_i32 s36, 0x3fff
	s_mov_b64 s[12:13], 0xdd00000
	s_mov_b64 s[14:15], 0xe500000
	s_mov_b32 s37, 0xdd00000
	s_mov_b32 s38, 0xe500000
	s_branch .LBB0_976

; __global__ void __launch_bounds__(BLOCK_THREADS, 2) mega(Params p_unused) {
;     __shared__ __attribute__((aligned(16))) char lds[LDS_BYTES];
	.amdhsa_kernel _Z4mega6Params
		.amdhsa_group_segment_fixed_size 147520
		.amdhsa_private_segment_fixed_size 0
		.amdhsa_kernarg_size 480
		.amdhsa_user_sgpr_count 2
		.amdhsa_user_sgpr_dispatch_ptr 0
		.amdhsa_user_sgpr_queue_ptr 0
		.amdhsa_user_sgpr_kernarg_segment_ptr 1
		.amdhsa_user_sgpr_dispatch_id 0
		.amdhsa_user_sgpr_kernarg_preload_length 0
		.amdhsa_user_sgpr_kernarg_preload_offset 0
		.amdhsa_user_sgpr_private_segment_size 0
		.amdhsa_uses_dynamic_stack 0
		.amdhsa_enable_private_segment 0
		.amdhsa_system_sgpr_workgroup_id_x 1
		.amdhsa_system_sgpr_workgroup_id_y 0
		.amdhsa_system_sgpr_workgroup_id_z 0
		.amdhsa_system_sgpr_workgroup_info 0
		.amdhsa_system_vgpr_workitem_id 2
		.amdhsa_next_free_vgpr 256
		.amdhsa_next_free_sgpr 100
		.amdhsa_accum_offset 256
		.amdhsa_reserve_vcc 1
		.amdhsa_float_round_mode_32 0
		.amdhsa_float_round_mode_16_64 0
		.amdhsa_float_denorm_mode_32 3
		.amdhsa_float_denorm_mode_16_64 3
		.amdhsa_dx10_clamp 1
		.amdhsa_ieee_mode 1
		.amdhsa_fp16_overflow 0
		.amdhsa_tg_split 0
		.amdhsa_exception_fp_ieee_invalid_op 0
		.amdhsa_exception_fp_denorm_src 0
		.amdhsa_exception_fp_ieee_div_zero 0
		.amdhsa_exception_fp_ieee_overflow 0
		.amdhsa_exception_fp_ieee_underflow 0
		.amdhsa_exception_fp_ieee_inexact 0
		.amdhsa_exception_int_div_zero 0
	.end_amdhsa_kernel

; __global__ void __launch_bounds__(BLOCK_THREADS, 2) mega(Params p_unused) {
;     __shared__ __attribute__((aligned(16))) char lds[LDS_BYTES];
amdhsa.kernels:
  - .agpr_count:     0
    .args:
      - .offset:         0
        .size:           224
        .value_kind:     by_value
      - .offset:         224
        .size:           4
        .value_kind:     hidden_block_count_x
      - .offset:         228
        .size:           4
        .value_kind:     hidden_block_count_y
      - .offset:         232
        .size:           4
        .value_kind:     hidden_block_count_z
      - .offset:         236
        .size:           2
        .value_kind:     hidden_group_size_x
      - .offset:         238
        .size:           2
        .value_kind:     hidden_group_size_y
      - .offset:         240
        .size:           2
        .value_kind:     hidden_group_size_z
      - .offset:         242
        .size:           2
        .value_kind:     hidden_remainder_x
      - .offset:         244
        .size:           2
        .value_kind:     hidden_remainder_y
      - .offset:         246
        .size:           2
        .value_kind:     hidden_remainder_z
      - .offset:         264
        .size:           8
        .value_kind:     hidden_global_offset_x
      - .offset:         272
        .size:           8
        .value_kind:     hidden_global_offset_y
      - .offset:         280
        .size:           8
        .value_kind:     hidden_global_offset_z
      - .offset:         288
        .size:           2
        .value_kind:     hidden_grid_dims
      - .offset:         312
        .size:           8
        .value_kind:     hidden_multigrid_sync_arg
    .group_segment_fixed_size: 147520
    .kernarg_segment_align: 8
    .kernarg_segment_size: 480
    .language:       OpenCL C
    .language_version:
      - 2
      - 0
    .max_flat_workgroup_size: 512
    .name:           _Z4mega6Params
    .private_segment_fixed_size: 0
    .sgpr_count:     106
    .sgpr_spill_count: 19
    .symbol:         _Z4mega6Params.kd
    .uniform_work_group_size: 1
    .uses_dynamic_stack: false
    .vgpr_count:     256
    .vgpr_spill_count: 0
    .wavefront_size: 64
